# norm_mod_bf loops (P1 layer 1 and P5): next iteration's first row prefetched one block early, with an explicit vmcnt(0) at the loop exit
# speedup vs baseline: 1.0097x; 1.0065x over previous
; __device__ __forceinline__ int otid() { int t = threadIdx.x; asm volatile("" : "+v"(t)); return t; }
; __device__ NOINL void norm_mod_bf_phase(const bf16_t* xb, int nrows, const float* g, const float* mod  , int si, bf16_t* hb) {
;     const int tid = otid(), w = tid >> 6, lane = tid & 63;
;     const int stride = gridDim.x * 8;
;     for (int row = blockIdx.x * 8 + w; row < nrows; row += 2 * stride) {
;         u32x4 q[2][2]; int rows[2] = {row, row + stride};
; #pragma unroll
;         for (int u = 0; u < 2; ++u)
;             if (rows[u] < nrows) {
; #pragma unroll
;                 for (int j = 0; j < 2; ++j) q[u][j] = *(const u32x4*)(xb + (size_t)rows[u] * DM + 8 * lane + 512 * j);
.LBB0_280:
	s_andn2_b64 vcc, exec, s[40:41]
	s_cbranch_vccnz .LBB0_318
	v_mov_b32_e32 v0, v202
	v_readlane_b32 s0, v254, 9
	v_ashrrev_i32_e32 v2, 6, v0
	s_nop 0
	v_add_u32_e32 v36, s0, v2
	v_cmp_gt_i32_e32 vcc, s87, v36
	s_and_saveexec_b64 s[40:41], vcc
	s_cbranch_execz .LBB0_288
	v_lshlrev_b32_e32 v0, 3, v0
	v_and_b32_e32 v2, 0x1f8, v0
	v_readlane_b32 s28, v254, 16
	v_lshlrev_b32_e32 v0, 1, v2
	v_readlane_b32 s30, v254, 18
	v_readlane_b32 s31, v254, 19
	v_cmp_lt_i32_e32 vcc, v210, v204
	v_readlane_b32 s0, v252, 28
	v_lshl_add_u64 v[24:25], s[30:31], 0, v[0:1]
	v_cndmask_b32_e32 v0, v203, v210, vcc
	v_cmp_lt_i32_e32 vcc, v209, v204
	v_lshlrev_b32_e32 v3, 2, v0
	v_readlane_b32 s1, v252, 29
	v_cndmask_b32_e32 v0, v203, v209, vcc
	v_cmp_lt_i32_e32 vcc, v208, v204
	v_lshlrev_b32_e32 v38, 2, v0
	v_or_b32_e32 v8, 0x200, v2
	v_cndmask_b32_e32 v0, v203, v208, vcc
	v_cmp_lt_i32_e32 vcc, v207, v204
	v_lshlrev_b32_e32 v39, 2, v0
	s_mov_b64 s[48:49], 0
	v_cndmask_b32_e32 v0, v203, v207, vcc
	v_cmp_lt_i32_e32 vcc, v206, v204
	v_lshlrev_b32_e32 v40, 2, v0
	v_lshlrev_b32_e32 v30, 2, v8
	v_cndmask_b32_e32 v0, v203, v206, vcc
	v_cmp_lt_i32_e32 vcc, v205, v204
	v_lshlrev_b32_e32 v41, 2, v0
	v_readlane_b32 s29, v254, 17
	v_cndmask_b32_e32 v0, v203, v205, vcc
	v_lshlrev_b32_e32 v42, 2, v0
	v_lshlrev_b32_e32 v0, 2, v2
	v_lshl_add_u64 v[26:27], s[0:1], 0, v[0:1]
	v_lshlrev_b32_e32 v0, 2, v8
	v_lshl_add_u64 v[28:29], s[0:1], 0, v[0:1]
	v_mov_b32_e32 v104, v36
	v_ashrrev_i32_e32 v105, 31, v104
	v_lshlrev_b64 v[104:105], 11, v[104:105]
	v_lshl_add_u64 v[104:105], v[24:25], 0, v[104:105]
	global_load_dwordx4 v[96:99], v[104:105], off
	global_load_dwordx4 v[100:103], v[104:105], off offset:1024
	s_branch .LBB0_284

; __device__ __forceinline__ unsigned pk2(float lo, float hi) { const f32v2_t f = {lo, hi}; const bf16v2_t b = __builtin_convertvector(f, bf16v2_t); return __builtin_bit_cast(unsigned, b); }
; __device__ NOINL void norm_mod_bf_phase(const bf16_t* xb, int nrows, const float* g, const float* mod  , int si, bf16_t* hb) {
;     ...
;     for (int row = blockIdx.x * 8 + w; row < nrows; row += 2 * stride) {
;         u32x4 q[2][2]; int rows[2] = {row, row + stride};
; #pragma unroll
;         for (int u = 0; u < 2; ++u)
;             if (rows[u] < nrows) {
; #pragma unroll
;                 for (int j = 0; j < 2; ++j) q[u][j] = *(const u32x4*)(xb + (size_t)rows[u] * DM + 8 * lane + 512 * j);
;             }
; #pragma unroll
;         for (int u = 0; u < 2; ++u)
;             if (rows[u] < nrows) {
;                 float v[2][8]; float ss = 0.f;
; #pragma unroll
;                 for (int j = 0; j < 2; ++j) { unpack8(q[u][j], v[j]);
; #pragma unroll
;                     for (int e = 0; e < 8; ++e) ss += v[j][e] * v[j][e]; }
;                 const float inv = rsqrtf(wave_sum(ss) * (1.f / DM) + 1e-6f);
;                 const float* sh = mod + (size_t)(rows[u] >> 11) * 6144 + si * 1024; const float* scp = sh + 1024;
; #pragma unroll
;                 for (int j = 0; j < 2; ++j) {
;                     const int c = 8 * lane + 512 * j;
;                     float o[8];
; #pragma unroll
;                     for (int h4 = 0; h4 < 2; ++h4) {
;                         const f32x4 gv = *(const f32x4*)(g + c + 4 * h4), sv = *(const f32x4*)(scp + c + 4 * h4), hv = *(const f32x4*)(sh + c + 4 * h4);
; #pragma unroll
;                         for (int e = 0; e < 4; ++e) o[4 * h4 + e] = v[j][4 * h4 + e] * inv * gv[e] * (1.f + sv[e]) + hv[e];
;                     }
;                     u32x4 pk; pk.x = pk2(o[0], o[1]); pk.y = pk2(o[2], o[3]); pk.z = pk2(o[4], o[5]); pk.w = pk2(o[6], o[7]);
;                     *(u32x4*)(hb + (size_t)rows[u] * DM + c) = pk;
;                 }
.LBB0_284:
	v_ashrrev_i32_e32 v37, 31, v36
	v_lshlrev_b64 v[16:17], 11, v[36:37]
	v_lshl_add_u64 v[34:35], v[24:25], 0, v[16:17]
	v_add_u32_e32 v32, s11, v36
	v_cmp_gt_i32_e32 vcc, s87, v32
	v_ashrrev_i32_e32 v33, 31, v32
	s_and_saveexec_b64 s[46:47], vcc
	s_cbranch_execz .LBB0_286
	v_lshlrev_b64 v[8:9], 11, v[32:33]
	v_lshl_add_u64 v[8:9], v[24:25], 0, v[8:9]
	global_load_dwordx4 v[12:15], v[8:9], off
	s_nop 0
	global_load_dwordx4 v[8:11], v[8:9], off offset:1024
.LBB0_286:
	s_or_b64 exec, exec, s[46:47]
	v_ashrrev_i32_e32 v0, 11, v36
	v_readlane_b32 s0, v255, 30
	v_mul_hi_i32_i24_e32 v37, 0x6000, v0
	v_mul_i32_i24_e32 v36, 0x6000, v0
	v_readlane_b32 s1, v255, 31
	v_lshlrev_b32_e32 v0, 2, v2
	v_lshl_add_u64 v[36:37], s[0:1], 0, v[36:37]
	s_mov_b64 s[0:1], 0x1000
	v_lshl_add_u64 v[68:69], v[36:37], 0, s[0:1]
	v_lshl_add_u64 v[56:57], v[68:69], 0, v[0:1]
	v_lshl_add_u64 v[36:37], v[36:37], 0, v[0:1]
	global_load_dwordx4 v[44:47], v[26:27], off offset:16
	global_load_dwordx4 v[166:169], v[26:27], off
	global_load_dwordx4 v[170:173], v[56:57], off offset:16
	global_load_dwordx4 v[174:177], v[56:57], off
	global_load_dwordx4 v[178:181], v[36:37], off offset:16
	global_load_dwordx4 v[186:189], v[36:37], off
	v_mov_b32_e32 v183, v1
	v_mov_b32_e32 v182, v30
	v_lshl_add_u64 v[190:191], v[68:69], 0, v[182:183]
	global_load_dwordx4 v[192:195], v[28:29], off
	global_load_dwordx4 v[196:199], v[190:191], off
	global_load_dwordx4 v[234:237], v[28:29], off offset:16
	global_load_dwordx4 v[238:241], v[190:191], off offset:16
	global_load_dwordx4 v[242:245], v[36:37], off offset:2048
	global_load_dwordx4 v[246:249], v[36:37], off offset:2064
	s_waitcnt vmcnt(12)
	v_mov_b32_e32 v20, v96
	v_mov_b32_e32 v21, v97
	v_mov_b32_e32 v22, v98
	v_mov_b32_e32 v23, v99
	v_mov_b32_e32 v16, v100
	v_mov_b32_e32 v17, v101
	v_mov_b32_e32 v18, v102
	v_mov_b32_e32 v19, v103
	v_lshlrev_b32_e32 v80, 16, v20
	s_nop 0
	s_nop 0
	v_and_b32_e32 v81, 0xffff0000, v20
	v_lshlrev_b32_e32 v76, 16, v21
	v_and_b32_e32 v77, 0xffff0000, v21
	v_pk_mul_f32 v[20:21], v[80:81], v[80:81]
	v_pk_mul_f32 v[78:79], v[76:77], v[76:77]
	v_add_f32_e32 v20, v20, v21
	v_lshlrev_b32_e32 v74, 16, v22
	v_and_b32_e32 v75, 0xffff0000, v22
	v_add_f32_e32 v20, v78, v20
	v_lshlrev_b32_e32 v70, 16, v23
	v_and_b32_e32 v71, 0xffff0000, v23
	v_pk_mul_f32 v[22:23], v[74:75], v[74:75]
	v_add_f32_e32 v20, v79, v20
	v_add_f32_e32 v20, v22, v20
	v_pk_mul_f32 v[72:73], v[70:71], v[70:71]
	v_add_f32_e32 v20, v23, v20
	v_lshlrev_b32_e32 v92, 16, v16
	v_and_b32_e32 v93, 0xffff0000, v16
	v_add_f32_e32 v20, v72, v20
	v_lshlrev_b32_e32 v88, 16, v17
	v_and_b32_e32 v89, 0xffff0000, v17
	v_pk_mul_f32 v[16:17], v[92:93], v[92:93]
	v_add_f32_e32 v20, v73, v20
	v_add_f32_e32 v16, v16, v20
	v_pk_mul_f32 v[90:91], v[88:89], v[88:89]
	v_add_f32_e32 v16, v17, v16
	v_lshlrev_b32_e32 v86, 16, v18
	v_and_b32_e32 v87, 0xffff0000, v18
	v_add_f32_e32 v16, v90, v16
	v_lshlrev_b32_e32 v82, 16, v19
	v_and_b32_e32 v83, 0xffff0000, v19
	v_pk_mul_f32 v[18:19], v[86:87], v[86:87]
	v_add_f32_e32 v16, v91, v16
	v_add_f32_e32 v16, v18, v16
	v_pk_mul_f32 v[84:85], v[82:83], v[82:83]
	v_add_f32_e32 v16, v19, v16
	v_add_f32_e32 v16, v84, v16
	v_add_f32_e32 v16, v85, v16
	ds_bpermute_b32 v17, v3, v16
	s_waitcnt lgkmcnt(0)
	v_add_f32_e32 v16, v16, v17
	ds_bpermute_b32 v17, v38, v16
	s_waitcnt lgkmcnt(0)
	v_add_f32_e32 v16, v16, v17
	ds_bpermute_b32 v17, v39, v16
	s_waitcnt lgkmcnt(0)
	v_add_f32_e32 v16, v16, v17
	ds_bpermute_b32 v17, v40, v16
	s_waitcnt lgkmcnt(0)
	v_add_f32_e32 v16, v16, v17
	ds_bpermute_b32 v17, v41, v16
	s_waitcnt lgkmcnt(0)
	v_add_f32_e32 v16, v16, v17
	ds_bpermute_b32 v17, v42, v16
	s_waitcnt lgkmcnt(0)
	v_add_f32_e32 v16, v16, v17
	v_fmamk_f32 v16, v16, 0x3a800000, v211
	v_mul_f32_e32 v17, 0x4b800000, v16
	v_cmp_gt_f32_e64 s[46:47], s79, v16
	s_waitcnt vmcnt(9)
	v_pk_add_f32 v[22:23], v[170:171], 1.0 op_sel_hi:[1,0]
	v_cndmask_b32_e64 v16, v16, v17, s[46:47]
	v_rsq_f32_e32 v16, v16
	s_nop 0
	v_mul_f32_e32 v17, 0x45800000, v16
	v_cndmask_b32_e64 v72, v16, v17, s[46:47]
	v_pk_mul_f32 v[20:21], v[72:73], v[74:75] op_sel_hi:[0,1]
	v_pk_mul_f32 v[20:21], v[44:45], v[20:21]
	v_pk_mul_f32 v[16:17], v[72:73], v[80:81] op_sel_hi:[0,1]
	v_pk_mul_f32 v[18:19], v[72:73], v[76:77] op_sel_hi:[0,1]
	s_waitcnt vmcnt(7)
	v_pk_fma_f32 v[20:21], v[22:23], v[20:21], v[178:179]
	v_pk_mul_f32 v[22:23], v[72:73], v[70:71] op_sel_hi:[0,1]
	v_pk_mul_f32 v[16:17], v[166:167], v[16:17]
	v_pk_mul_f32 v[18:19], v[168:169], v[18:19]
	v_pk_add_f32 v[44:45], v[176:177], 1.0 op_sel_hi:[1,0]
	v_pk_add_f32 v[48:49], v[174:175], 1.0 op_sel_hi:[1,0]
	v_pk_add_f32 v[50:51], v[172:173], 1.0 op_sel_hi:[1,0]
	v_pk_mul_f32 v[22:23], v[46:47], v[22:23]
	s_waitcnt vmcnt(6)
	v_pk_fma_f32 v[16:17], v[48:49], v[16:17], v[186:187]
	v_pk_fma_f32 v[18:19], v[44:45], v[18:19], v[188:189]
	v_pk_fma_f32 v[22:23], v[50:51], v[22:23], v[180:181]
	v_cvt_pk_bf16_f32 v16, v16, v17
	v_cvt_pk_bf16_f32 v17, v18, v19
	v_cvt_pk_bf16_f32 v18, v20, v21
	v_cvt_pk_bf16_f32 v19, v22, v23
	global_store_dwordx4 v[34:35], v[16:19], off
	s_nop 0
	v_pk_mul_f32 v[36:37], v[72:73], v[92:93] op_sel_hi:[0,1]
	v_pk_mul_f32 v[60:61], v[72:73], v[88:89] op_sel_hi:[0,1]
	v_pk_mul_f32 v[62:63], v[72:73], v[86:87] op_sel_hi:[0,1]
	v_pk_mul_f32 v[64:65], v[72:73], v[82:83] op_sel_hi:[0,1]
	s_waitcnt vmcnt(6)
	v_pk_mul_f32 v[16:17], v[192:193], v[36:37]
	s_waitcnt vmcnt(5)
	v_pk_add_f32 v[20:21], v[196:197], 1.0 op_sel_hi:[1,0]
	v_pk_mul_f32 v[18:19], v[194:195], v[60:61]
	v_pk_add_f32 v[22:23], v[198:199], 1.0 op_sel_hi:[1,0]
	s_waitcnt vmcnt(4)
	v_pk_mul_f32 v[36:37], v[62:63], v[234:235]
	s_waitcnt vmcnt(3)
	v_pk_add_f32 v[44:45], v[238:239], 1.0 op_sel_hi:[1,0]
	v_pk_mul_f32 v[46:47], v[64:65], v[236:237]
	v_pk_add_f32 v[48:49], v[240:241], 1.0 op_sel_hi:[1,0]
	s_waitcnt vmcnt(2)
	v_pk_fma_f32 v[16:17], v[20:21], v[16:17], v[242:243]
	v_pk_fma_f32 v[18:19], v[22:23], v[18:19], v[244:245]
	s_waitcnt vmcnt(1)
	v_pk_fma_f32 v[20:21], v[36:37], v[44:45], v[246:247]
	v_pk_fma_f32 v[22:23], v[46:47], v[48:49], v[248:249]
	v_cvt_pk_bf16_f32 v16, v16, v17
	v_cvt_pk_bf16_f32 v17, v18, v19
	v_cvt_pk_bf16_f32 v18, v20, v21
	v_cvt_pk_bf16_f32 v19, v22, v23
	global_store_dwordx4 v[34:35], v[16:19], off offset:1024
	s_and_saveexec_b64 s[46:47], vcc
	s_cbranch_execz .LBB0_283
; __device__ __forceinline__ unsigned pk2(float lo, float hi) { const f32v2_t f = {lo, hi}; const bf16v2_t b = __builtin_convertvector(f, bf16v2_t); return __builtin_bit_cast(unsigned, b); }
; __device__ NOINL void norm_mod_bf_phase(const bf16_t* xb, int nrows, const float* g, const float* mod  , int si, bf16_t* hb) {
;     ...
; #pragma unroll
;         for (int u = 0; u < 2; ++u)
;             if (rows[u] < nrows) {
;                 float v[2][8]; float ss = 0.f;
; #pragma unroll
;                 for (int j = 0; j < 2; ++j) { unpack8(q[u][j], v[j]);
; #pragma unroll
;                     for (int e = 0; e < 8; ++e) ss += v[j][e] * v[j][e]; }
;                 const float inv = rsqrtf(wave_sum(ss) * (1.f / DM) + 1e-6f);
;                 const float* sh = mod + (size_t)(rows[u] >> 11) * 6144 + si * 1024; const float* scp = sh + 1024;
; #pragma unroll
;                 for (int j = 0; j < 2; ++j) {
;                     const int c = 8 * lane + 512 * j;
;                     float o[8];
; #pragma unroll
;                     for (int h4 = 0; h4 < 2; ++h4) {
;                         const f32x4 gv = *(const f32x4*)(g + c + 4 * h4), sv = *(const f32x4*)(scp + c + 4 * h4), hv = *(const f32x4*)(sh + c + 4 * h4);
; #pragma unroll
;                         for (int e = 0; e < 4; ++e) o[4 * h4 + e] = v[j][4 * h4 + e] * inv * gv[e] * (1.f + sv[e]) + hv[e];
;                     }
;                     u32x4 pk; pk.x = pk2(o[0], o[1]); pk.y = pk2(o[2], o[3]); pk.z = pk2(o[4], o[5]); pk.w = pk2(o[6], o[7]);
;                     *(u32x4*)(hb + (size_t)rows[u] * DM + c) = pk;
;                 }
	v_ashrrev_i32_e32 v16, 11, v32
	v_readlane_b32 s0, v255, 30
	v_mul_hi_i32_i24_e32 v17, 0x6000, v16
	v_mul_i32_i24_e32 v16, 0x6000, v16
	v_readlane_b32 s1, v255, 31
	v_lshlrev_b32_e32 v72, 16, v12
	v_and_b32_e32 v73, 0xffff0000, v12
	v_lshl_add_u64 v[16:17], s[0:1], 0, v[16:17]
	s_mov_b64 s[0:1], 0x1000
	v_lshl_add_u64 v[56:57], v[16:17], 0, s[0:1]
	v_lshl_add_u64 v[44:45], v[56:57], 0, v[0:1]
	v_lshl_add_u64 v[58:59], v[16:17], 0, v[0:1]
	global_load_dwordx4 v[166:169], v[26:27], off offset:16
	global_load_dwordx4 v[170:173], v[26:27], off
	global_load_dwordx4 v[174:177], v[44:45], off offset:16
	global_load_dwordx4 v[178:181], v[44:45], off
	global_load_dwordx4 v[186:189], v[58:59], off offset:16
	global_load_dwordx4 v[190:193], v[58:59], off
	v_mov_b32_e32 v31, v1
	v_lshl_add_u64 v[182:183], v[56:57], 0, v[30:31]
	global_load_dwordx4 v[194:197], v[28:29], off
	global_load_dwordx4 v[198:201], v[182:183], off
	global_load_dwordx4 v[234:237], v[28:29], off offset:16
	global_load_dwordx4 v[238:241], v[182:183], off offset:16
	global_load_dwordx4 v[242:245], v[58:59], off offset:2048
	global_load_dwordx4 v[246:249], v[58:59], off offset:2064
	s_nop 0
	s_nop 0
	v_add_u32_e32 v104, s11, v32
	v_ashrrev_i32_e32 v105, 31, v104
	v_lshlrev_b64 v[104:105], 11, v[104:105]
	v_lshl_add_u64 v[104:105], v[24:25], 0, v[104:105]
	global_load_dwordx4 v[96:99], v[104:105], off
	global_load_dwordx4 v[100:103], v[104:105], off offset:1024
	v_lshlrev_b32_e32 v68, 16, v13
	v_and_b32_e32 v69, 0xffff0000, v13
	v_pk_mul_f32 v[74:75], v[72:73], v[72:73]
	v_pk_mul_f32 v[70:71], v[68:69], v[68:69]
	v_add_f32_e32 v0, v74, v75
	v_lshlrev_b32_e32 v64, 16, v14
	v_and_b32_e32 v65, 0xffff0000, v14
	v_add_f32_e32 v0, v70, v0
	v_pk_mul_f32 v[66:67], v[64:65], v[64:65]
	v_add_f32_e32 v0, v71, v0
	v_lshlrev_b32_e32 v60, 16, v15
	v_and_b32_e32 v61, 0xffff0000, v15
	v_add_f32_e32 v0, v66, v0
	v_pk_mul_f32 v[62:63], v[60:61], v[60:61]
	v_add_f32_e32 v0, v67, v0
	v_lshlrev_b32_e32 v88, 16, v8
	v_and_b32_e32 v89, 0xffff0000, v8
	v_add_f32_e32 v0, v62, v0
	v_pk_mul_f32 v[90:91], v[88:89], v[88:89]
	v_add_f32_e32 v0, v63, v0
	v_lshlrev_b32_e32 v84, 16, v9
	v_and_b32_e32 v85, 0xffff0000, v9
	v_add_f32_e32 v0, v90, v0
	v_pk_mul_f32 v[86:87], v[84:85], v[84:85]
	v_add_f32_e32 v0, v91, v0
	v_lshlrev_b32_e32 v80, 16, v10
	v_and_b32_e32 v81, 0xffff0000, v10
	v_add_f32_e32 v0, v86, v0
	v_pk_mul_f32 v[82:83], v[80:81], v[80:81]
	v_add_f32_e32 v0, v87, v0
	v_lshlrev_b32_e32 v76, 16, v11
	v_and_b32_e32 v77, 0xffff0000, v11
	v_add_f32_e32 v0, v82, v0
	v_pk_mul_f32 v[78:79], v[76:77], v[76:77]
	v_add_f32_e32 v0, v83, v0
	v_add_f32_e32 v0, v78, v0
	v_add_f32_e32 v0, v79, v0
	ds_bpermute_b32 v43, v3, v0
	v_lshlrev_b64 v[62:63], 11, v[32:33]
	v_lshl_add_u64 v[62:63], v[24:25], 0, v[62:63]
	s_waitcnt lgkmcnt(0)
	v_add_f32_e32 v0, v0, v43
	ds_bpermute_b32 v43, v38, v0
	s_waitcnt lgkmcnt(0)
	v_add_f32_e32 v0, v0, v43
	ds_bpermute_b32 v43, v39, v0
	s_waitcnt lgkmcnt(0)
	v_add_f32_e32 v0, v0, v43
	ds_bpermute_b32 v43, v40, v0
	s_waitcnt lgkmcnt(0)
	v_add_f32_e32 v0, v0, v43
	ds_bpermute_b32 v43, v41, v0
	s_waitcnt lgkmcnt(0)
	v_add_f32_e32 v0, v0, v43
	ds_bpermute_b32 v43, v42, v0
	s_waitcnt lgkmcnt(0)
	v_add_f32_e32 v0, v0, v43
	v_fmamk_f32 v0, v0, 0x3a800000, v211
	v_mul_f32_e32 v43, 0x4b800000, v0
	v_cmp_gt_f32_e32 vcc, s79, v0
	s_waitcnt vmcnt(11)
	v_pk_add_f32 v[34:35], v[174:175], 1.0 op_sel_hi:[1,0]
	s_waitcnt vmcnt(10)
	v_pk_add_f32 v[46:47], v[180:181], 1.0 op_sel_hi:[1,0]
	v_cndmask_b32_e32 v0, v0, v43, vcc
	v_rsq_f32_e32 v0, v0
	v_pk_add_f32 v[44:45], v[178:179], 1.0 op_sel_hi:[1,0]
	v_pk_add_f32 v[36:37], v[176:177], 1.0 op_sel_hi:[1,0]
	v_mul_f32_e32 v31, 0x45800000, v0
	v_cndmask_b32_e32 v0, v0, v31, vcc
	v_pk_mul_f32 v[64:65], v[0:1], v[64:65] op_sel_hi:[0,1]
	v_pk_mul_f32 v[16:17], v[166:167], v[64:65]
	v_pk_mul_f32 v[66:67], v[0:1], v[72:73] op_sel_hi:[0,1]
	v_pk_mul_f32 v[68:69], v[0:1], v[68:69] op_sel_hi:[0,1]
	s_waitcnt vmcnt(9)
	v_pk_fma_f32 v[34:35], v[34:35], v[16:17], v[186:187]
	v_pk_mul_f32 v[16:17], v[0:1], v[60:61] op_sel_hi:[0,1]
	v_pk_mul_f32 v[20:21], v[170:171], v[66:67]
	v_pk_mul_f32 v[22:23], v[172:173], v[68:69]
	v_pk_mul_f32 v[16:17], v[168:169], v[16:17]
	s_waitcnt vmcnt(8)
	v_pk_fma_f32 v[20:21], v[44:45], v[20:21], v[190:191]
	v_pk_fma_f32 v[22:23], v[46:47], v[22:23], v[192:193]
	v_pk_fma_f32 v[36:37], v[36:37], v[16:17], v[188:189]
	v_cvt_pk_bf16_f32 v16, v20, v21
	v_cvt_pk_bf16_f32 v17, v22, v23
	v_cvt_pk_bf16_f32 v18, v34, v35
	v_cvt_pk_bf16_f32 v19, v36, v37
	global_store_dwordx4 v[62:63], v[16:19], off
	s_nop 0
	v_pk_mul_f32 v[56:57], v[0:1], v[88:89] op_sel_hi:[0,1]
	v_pk_mul_f32 v[58:59], v[0:1], v[84:85] op_sel_hi:[0,1]
	v_pk_mul_f32 v[60:61], v[0:1], v[80:81] op_sel_hi:[0,1]
	v_pk_mul_f32 v[64:65], v[0:1], v[76:77] op_sel_hi:[0,1]
	s_waitcnt vmcnt(8)
	v_pk_mul_f32 v[16:17], v[194:195], v[56:57]
	s_waitcnt vmcnt(7)
	v_pk_add_f32 v[20:21], v[198:199], 1.0 op_sel_hi:[1,0]
	v_pk_mul_f32 v[18:19], v[196:197], v[58:59]
	v_pk_add_f32 v[22:23], v[200:201], 1.0 op_sel_hi:[1,0]
	s_waitcnt vmcnt(6)
	v_pk_mul_f32 v[34:35], v[60:61], v[234:235]
	s_waitcnt vmcnt(5)
	v_pk_add_f32 v[44:45], v[238:239], 1.0 op_sel_hi:[1,0]
	v_pk_mul_f32 v[36:37], v[64:65], v[236:237]
	v_pk_add_f32 v[46:47], v[240:241], 1.0 op_sel_hi:[1,0]
	s_waitcnt vmcnt(4)
	v_pk_fma_f32 v[16:17], v[20:21], v[16:17], v[242:243]
	v_pk_fma_f32 v[18:19], v[22:23], v[18:19], v[244:245]
	s_waitcnt vmcnt(3)
	v_pk_fma_f32 v[20:21], v[34:35], v[44:45], v[246:247]
	v_pk_fma_f32 v[22:23], v[36:37], v[46:47], v[248:249]
	v_cvt_pk_bf16_f32 v16, v16, v17
	v_cvt_pk_bf16_f32 v17, v18, v19
	v_cvt_pk_bf16_f32 v18, v20, v21
	v_cvt_pk_bf16_f32 v19, v22, v23
	global_store_dwordx4 v[62:63], v[16:19], off offset:1024
	s_branch .LBB0_283
; __device__ __forceinline__ int otid() { int t = threadIdx.x; asm volatile("" : "+v"(t)); return t; }
;     const int tid = otid(), w = tid >> 6, lane = tid & 63;
;     const int stride = gridDim.x * 8;
;     for (int row = first + blockIdx.x * 8 + w; row < nrows; row += 2 * stride) {
;         f32x4 v[2][4]; float ss[2] = {0.f, 0.f}; int rows[2] = {row, row + stride};
; #pragma unroll
;         for (int u = 0; u < 2; ++u) {
;             if (rows[u] < nrows) {
;                 const bool il = rows[u] < NLAT;
;                 const float* xr = il ? lat + (size_t)rows[u] * DM : ctxp + (size_t)(rows[u] - NLAT) * DM;
; #pragma unroll
;                 for (int j = 0; j < 4; ++j) v[u][j] = *(const f32x4*)(xr + 4 * lane + 256 * j);
; __global__ void __launch_bounds__(512) mega_fwd(Params p) {
;     ...
;                 norm_mod_bf_phase(p.hbuf, NLAT, p.norm1_g + l * DM, mod, 0, p.hbuf);
;                 if (tailk) norm_mod_phase(xl, xc, NTOK, p.norm1_g + l * DM, mod, 0, p.hbuf, (const float*)p.hyT, p.modbuf + 16 * 6144 + 5 * 1024, nullptr, NLAT);
;                 else norm_mod_phase(xl, xc, NTOK, p.norm1_g + l * DM, mod, 0, p.hbuf, nullptr, nullptr, nullptr, NLAT);
.LBB0_288:
	s_waitcnt vmcnt(0)
	s_or_b64 exec, exec, s[40:41]
	v_readlane_b32 s0, v252, 20
	v_readlane_b32 s1, v252, 21
	s_mov_b64 s[40:41], -1
	s_and_b64 vcc, exec, s[0:1]
	s_cbranch_vccz .LBB0_301
	v_mov_b32_e32 v3, v202
	v_readlane_b32 s0, v252, 30
	v_ashrrev_i32_e32 v8, 6, v3
	s_nop 0
	v_add_u32_e32 v2, s0, v8
	s_mov_b32 s0, 0x9000
	v_cmp_gt_i32_e32 vcc, s0, v2
	s_and_saveexec_b64 s[40:41], vcc
	s_cbranch_execz .LBB0_300
	v_lshlrev_b32_e32 v0, 2, v3
	v_and_b32_e32 v10, 0xfc, v0
	v_readlane_b32 s0, v252, 28
	v_or_b32_e32 v12, 0x100, v10
	v_lshlrev_b32_e32 v0, 2, v10
	v_readlane_b32 s1, v252, 29
	v_or_b32_e32 v14, 0x200, v10
	v_or_b32_e32 v16, 0x300, v10
	v_lshl_add_u64 v[40:41], s[0:1], 0, v[0:1]
	v_lshlrev_b32_e32 v0, 2, v12
	v_lshl_add_u64 v[42:43], s[0:1], 0, v[0:1]
	v_lshlrev_b32_e32 v0, 2, v14
	v_lshl_add_u64 v[44:45], s[0:1], 0, v[0:1]
	v_lshlrev_b32_e32 v0, 2, v16
	v_cmp_lt_i32_e32 vcc, v210, v204
	v_lshl_add_u64 v[46:47], s[0:1], 0, v[0:1]
	v_readlane_b32 s0, v254, 11
	v_cndmask_b32_e32 v0, v203, v210, vcc
	v_cmp_lt_i32_e32 vcc, v209, v204
	v_lshlrev_b32_e32 v64, 2, v0
	v_add_u32_e32 v48, s0, v8
	v_cndmask_b32_e32 v0, v203, v209, vcc
	v_cmp_lt_i32_e32 vcc, v208, v204
	v_lshlrev_b32_e32 v65, 2, v0
	v_readlane_b32 s28, v254, 16
	v_cndmask_b32_e32 v0, v203, v208, vcc
	v_cmp_lt_i32_e32 vcc, v207, v204
	v_lshlrev_b32_e32 v66, 2, v0
	v_ashrrev_i32_e32 v49, 31, v48
	v_cndmask_b32_e32 v0, v203, v207, vcc
	v_cmp_lt_i32_e32 vcc, v206, v204
	v_lshlrev_b32_e32 v67, 2, v0
	v_readlane_b32 s30, v254, 18
	v_cndmask_b32_e32 v0, v203, v206, vcc
	v_cmp_lt_i32_e32 vcc, v205, v204
	v_lshlrev_b32_e32 v68, 2, v0
	v_readlane_b32 s31, v254, 19
	v_cndmask_b32_e32 v0, v203, v205, vcc
	v_lshlrev_b32_e32 v69, 2, v0
	v_and_b32_e32 v0, 63, v3
	v_ashrrev_i32_e32 v3, 31, v2
	v_lshlrev_b64 v[8:9], 11, v[2:3]
	v_lshl_add_u64 v[52:53], s[30:31], 0, v[8:9]
	v_lshlrev_b64 v[8:9], 11, v[48:49]
	v_lshlrev_b32_e32 v50, 3, v0
	v_mov_b32_e32 v51, v1
	v_lshl_add_u64 v[54:55], s[30:31], 0, v[8:9]
	s_mov_b64 s[48:49], 0
	v_lshlrev_b32_e32 v0, 2, v10
	v_lshlrev_b32_e32 v56, 2, v12
	v_lshlrev_b32_e32 v58, 2, v14
	v_lshlrev_b32_e32 v60, 2, v16
	s_mov_b64 s[50:51], 0
	v_mov_b32_e32 v70, v2
	v_readlane_b32 s29, v254, 17
	s_branch .LBB0_293

; __device__ __forceinline__ int otid() { int t = threadIdx.x; asm volatile("" : "+v"(t)); return t; }
;     const int tid = otid(), w = tid >> 6, lane = tid & 63;
;     const int stride = gridDim.x * 8;
;     for (int row = first + blockIdx.x * 8 + w; row < nrows; row += 2 * stride) {
;         f32x4 v[2][4]; float ss[2] = {0.f, 0.f}; int rows[2] = {row, row + stride};
; #pragma unroll
;         for (int u = 0; u < 2; ++u) {
;             if (rows[u] < nrows) {
;                 const bool il = rows[u] < NLAT;
;                 const float* xr = il ? lat + (size_t)rows[u] * DM : ctxp + (size_t)(rows[u] - NLAT) * DM;
; #pragma unroll
;                 for (int j = 0; j < 4; ++j) v[u][j] = *(const f32x4*)(xr + 4 * lane + 256 * j);
; __global__ void __launch_bounds__(512) mega_fwd(Params p) {
;     ...
;         if (RUN && (PHM & 256)) {
;             norm_mod_bf_phase(p.proj, NLAT, p.norm2_g + l * DM, mod, 3, p.hbuf);
;             if (l == 0) {
;                 if (tailk) norm_mod_phase(p.out, p.ctx, Mf, p.norm2_g + l * DM, mod, 3, p.hbuf, (const float*)p.hyT, mod + 16 * 6144 + 2 * 1024, p.ctx_x, NLAT);
;                 else norm_mod_phase(p.out, p.ctx_x, Mf, p.norm2_g + l * DM, mod, 3, p.hbuf, nullptr, nullptr, nullptr, NLAT);
;             }
.LBB0_1637:
	s_waitcnt vmcnt(0)
	s_or_b64 exec, exec, s[46:47]
	v_readlane_b32 s0, v255, 25
	v_readlane_b32 s1, v255, 26
	s_andn2_b64 vcc, exec, s[0:1]
	s_cbranch_vccnz .LBB0_1690
	v_readlane_b32 s0, v255, 25
	v_readlane_b32 s1, v255, 26
	s_and_b64 s[0:1], s[0:1], exec
	s_mov_b32 s0, 0x9000
	s_cselect_b32 s3, s0, 0x8000
	v_readlane_b32 s0, v252, 20
	v_readlane_b32 s1, v252, 21
	s_mov_b64 s[44:45], -1
	s_and_b64 vcc, exec, s[0:1]
	s_cbranch_vccz .LBB0_1655
	v_mov_b32_e32 v8, v202
	v_readlane_b32 s0, v252, 30
	v_ashrrev_i32_e32 v0, 6, v8
	s_nop 0
	v_add_u32_e32 v2, s0, v0
	s_mov_b32 s0, 0x9000
	v_cmp_gt_i32_e32 vcc, s0, v2
	s_and_saveexec_b64 s[48:49], vcc
	s_cbranch_execz .LBB0_1654
	v_lshlrev_b32_e32 v0, 2, v8
	v_and_b32_e32 v40, 0xfc, v0
	v_readlane_b32 s0, v255, 30
	v_lshlrev_b32_e32 v0, 2, v40
	v_readlane_b32 s20, v254, 16
	v_readlane_b32 s1, v255, 31
	s_add_u32 s54, s0, 0x3000
	v_lshl_add_u64 v[48:49], s[40:41], 0, v[0:1]
	v_lshlrev_b32_e32 v0, 1, v40
	v_readlane_b32 s22, v254, 18
	v_readlane_b32 s23, v254, 19
	v_ashrrev_i32_e32 v3, 31, v2
	s_addc_u32 s55, s1, 0
	v_lshl_add_u64 v[50:51], s[22:23], 0, v[0:1]
	v_lshlrev_b64 v[10:11], 11, v[2:3]
	v_and_b32_e32 v0, 63, v8
	v_readlane_b32 s0, v254, 20
	v_lshl_or_b32 v10, v0, 3, v10
	v_readlane_b32 s1, v254, 21
	v_or_b32_e32 v42, 0x100, v40
	v_or_b32_e32 v44, 0x200, v40
	v_or_b32_e32 v46, 0x300, v40
	v_lshl_add_u64 v[52:53], s[0:1], 0, v[10:11]
	s_mov_b64 s[56:57], 0
	v_readlane_b32 s21, v254, 17
	s_branch .LBB0_1643
